# GEMM phases: K-loop without per-cluster s_setprio, one static s_setprio 1 for waves 4-7 over the whole phase (lever 4), on top of v37
# baseline (speedup 1.0000x reference)
.LBB0_901:
	v_readfirstlane_b32 s100, v220
	s_nop 3
	s_lshr_b32 s100, s100, 6
	s_cmp_ge_u32 s100, 4
	s_cbranch_scc0 .Lgemm_prio_done
	s_setprio 1

.LBB0_1479:
	s_setprio 0
	v_readlane_b32 s72, v254, 50
	v_readlane_b32 s70, v253, 37
	v_readlane_b32 s76, v253, 39
	v_readlane_b32 s90, v253, 41
	v_readlane_b32 s92, v253, 43
	v_readlane_b32 s73, v254, 51
	v_readlane_b32 s74, v254, 52
	v_readlane_b32 s75, v254, 53
	v_readlane_b32 s71, v253, 38
	v_readlane_b32 s77, v253, 40
	v_readlane_b32 s91, v253, 42
	v_readlane_b32 s93, v253, 44
	s_movk_i32 s96, 0x110
